# v019 plus loop-edge edit on all three GEMM K-loops: counter/pointer/address-select SALU moved from the SP1 head into the last load segment slack
# baseline (speedup 1.0000x reference)
; #define PG8_STAGE(bufoff, gbase, voff) do { _Pragma("unroll") for (int _i = 0; _i < 2; ++_i) \
;         __builtin_amdgcn_global_load_lds((const unsigned*)((const char*)(gbase) + (voff)[_i]), (PG8_LAS unsigned*)(lds + (bufoff) + ldsw + _i * 8192), 16, 0, 0); } while (0)
; #define PG8_LDA(dst, b, h) do { _Pragma("unroll") for (int m = 0; m < 4; ++m) _Pragma("unroll") for (int k = 0; k < 2; ++k) dst[m][k] = *(const PG8_LAS bf16x8*)(lds + PG8_SA(b, h) + aoff + m * 2048 + k * 1024); } while (0)
; #define PG8_LDB(dst, b, h) do { _Pragma("unroll") for (int n = 0; n < 2; ++n) _Pragma("unroll") for (int k = 0; k < 2; ++k) dst[n][k] = *(const PG8_LAS bf16x8*)(lds + PG8_SB(b, h) + boff + n * 2048 + k * 1024); } while (0)
; #define PG8_MMA(ai, bj, At, Bt) do { __builtin_amdgcn_s_setprio(1); _Pragma("unroll") for (int m = 0; m < 4; ++m) _Pragma("unroll") for (int n = 0; n < 2; ++n) _Pragma("unroll") for (int k = 0; k < 2; ++k) \
;         acc[ai][bj][m][n] = __builtin_amdgcn_mfma_f32_16x16x32_bf16(Bt[n][k], At[m][k], acc[ai][bj][m][n], 0, 0, 0); __builtin_amdgcn_s_setprio(0); } while (0)
; #define PG8_WAIT_V(n) asm volatile("s_waitcnt vmcnt(" #n ")" ::: "memory")
; #define PG8_WAIT_L(n) asm volatile("s_waitcnt lgkmcnt(" #n ")" ::: "memory")
; template <class Epi, class Sched, bool ALIGN_EPI = false, bool SP2 = false>
; __device__ __forceinline__ void gemm_phase(PG8_LAS unsigned char* lds, const Gemm g, const Sched& S, const Epi& E) {
;     ...
;             const bool last = (t == nt - 2);
;             const char* a1 = cA + (size_t)(t + 1) * kstep;
;             const char* a2 = last ? nA : cA + (size_t)(t + 2) * kstep; const char* b2 = last ? nB : cB + (size_t)(t + 2) * kstep;
;             const char* a3 = a2 + kstep; const char* b3 = b2 + kstep;
;             if (last && has_next) S.a_ready(nxt);
;             if constexpr (SP2) {
;             PG8_LDB(B0, 0, 0); PG8_LDB(B1, 0, 1); PG8_SCHED; PG8_LDA(At, 0, 0); PG8_STAGE(PG8_SA(1, 1), a1 + hstep, voffA);
;             PG8_WAIT_V(8); PG8_WAIT_L(0); PG8_BAR; PG8_MMA(0, 0, At, B0); PG8_MMA(0, 1, At, B1); PG8_BAR; PG8_SCHED;
;             PG8_LDA(At, 0, 1); PG8_STAGE(PG8_SB(0, 0), b2, voffB); PG8_STAGE(PG8_SB(0, 1), b2 + hstep, voffB); PG8_STAGE(PG8_SA(0, 0), a2, voffA);
;             PG8_WAIT_V(8); PG8_WAIT_L(0); PG8_BAR; PG8_MMA(1, 0, At, B0); PG8_MMA(1, 1, At, B1); PG8_BAR; PG8_SCHED;
.LBB0_117:
	s_add_u32 s50, s48, 0xfff80080
	s_addc_u32 s51, s49, -1
	s_add_i32 s61, 0, 0x10000
	s_cmp_eq_u32 s58, 28
	s_cselect_b32 s77, s1, s51
	s_cselect_b32 s76, s24, s50
	s_cselect_b32 s51, s25, s47
	s_cselect_b32 s50, s38, s39
	s_add_i32 s63, 0, 0x14000
.Lqkv_kbody:
	v_add_u32_e32 v0, s61, v234
	ds_read_b128 v[124:127], v0
	ds_read_b128 v[128:131], v0 offset:1024
	ds_read_b128 v[132:135], v0 offset:2048
	ds_read_b128 v[140:143], v0 offset:3072
	v_add_u32_e32 v0, s63, v234
	ds_read_b128 v[148:151], v0
	ds_read_b128 v[152:155], v0 offset:1024
	ds_read_b128 v[156:159], v0 offset:2048
	ds_read_b128 v[160:163], v0 offset:3072
	v_lshl_add_u64 v[2:3], s[48:49], 0, v[192:193]
	s_add_i32 m0, s82, 0xc000
	ds_read_b128 v[164:167], v235
	ds_read_b128 v[198:201], v235 offset:1024
	ds_read_b128 v[202:205], v235 offset:2048
	ds_read_b128 v[206:209], v235 offset:3072
	ds_read_b128 v[210:213], v235 offset:4096
	ds_read_b128 v[214:217], v235 offset:5120
	ds_read_b128 v[218:221], v235 offset:6144
	ds_read_b128 v[236:239], v235 offset:7168
	global_load_lds_dwordx4 v[2:3], off
	v_lshl_add_u64 v[2:3], s[48:49], 0, v[194:195]
	s_add_i32 m0, s82, 0xe000
	s_nop 0
	global_load_lds_dwordx4 v[2:3], off
	s_waitcnt vmcnt(8)
	s_waitcnt lgkmcnt(0)
	s_barrier
	s_setprio 1
	s_waitcnt lgkmcnt(0)
	v_mfma_f32_16x16x32_bf16 v[144:147], v[124:127], v[164:167], v[144:147]
	v_mfma_f32_16x16x32_bf16 v[136:139], v[132:135], v[164:167], v[136:139]
	v_mfma_f32_16x16x32_bf16 v[112:115], v[124:127], v[202:205], v[112:115]
	v_mfma_f32_16x16x32_bf16 v[108:111], v[132:135], v[202:205], v[108:111]
	v_mfma_f32_16x16x32_bf16 v[96:99], v[124:127], v[210:213], v[96:99]
	v_mfma_f32_16x16x32_bf16 v[92:95], v[132:135], v[210:213], v[92:95]
	v_mfma_f32_16x16x32_bf16 v[80:83], v[124:127], v[218:221], v[80:83]
	v_mfma_f32_16x16x32_bf16 v[76:79], v[132:135], v[218:221], v[76:79]
	v_mfma_f32_16x16x32_bf16 v[144:147], v[128:131], v[198:201], v[144:147]
	v_mfma_f32_16x16x32_bf16 v[136:139], v[140:143], v[198:201], v[136:139]
	v_mfma_f32_16x16x32_bf16 v[112:115], v[128:131], v[206:209], v[112:115]
	v_mfma_f32_16x16x32_bf16 v[108:111], v[140:143], v[206:209], v[108:111]
	v_mfma_f32_16x16x32_bf16 v[96:99], v[128:131], v[214:217], v[96:99]
	v_mfma_f32_16x16x32_bf16 v[92:95], v[140:143], v[214:217], v[92:95]
	v_mfma_f32_16x16x32_bf16 v[80:83], v[128:131], v[236:239], v[80:83]
	v_mfma_f32_16x16x32_bf16 v[76:79], v[140:143], v[236:239], v[76:79]
	s_setprio 0
	s_setprio 1
	v_mfma_f32_16x16x32_bf16 v[120:123], v[148:151], v[164:167], v[120:123]
	v_mfma_f32_16x16x32_bf16 v[116:119], v[156:159], v[164:167], v[116:119]
	v_mfma_f32_16x16x32_bf16 v[104:107], v[148:151], v[202:205], v[104:107]
	v_mfma_f32_16x16x32_bf16 v[100:103], v[156:159], v[202:205], v[100:103]
	v_mfma_f32_16x16x32_bf16 v[88:91], v[148:151], v[210:213], v[88:91]
	v_mfma_f32_16x16x32_bf16 v[84:87], v[156:159], v[210:213], v[84:87]
	v_mfma_f32_16x16x32_bf16 v[72:75], v[148:151], v[218:221], v[72:75]
	v_mfma_f32_16x16x32_bf16 v[68:71], v[156:159], v[218:221], v[68:71]
	v_mfma_f32_16x16x32_bf16 v[120:123], v[152:155], v[198:201], v[120:123]
	v_mfma_f32_16x16x32_bf16 v[116:119], v[160:163], v[198:201], v[116:119]
	v_mfma_f32_16x16x32_bf16 v[104:107], v[152:155], v[206:209], v[104:107]
	v_mfma_f32_16x16x32_bf16 v[100:103], v[160:163], v[206:209], v[100:103]
	v_mfma_f32_16x16x32_bf16 v[88:91], v[152:155], v[214:217], v[88:91]
	v_mfma_f32_16x16x32_bf16 v[84:87], v[160:163], v[214:217], v[84:87]
	v_mfma_f32_16x16x32_bf16 v[72:75], v[152:155], v[236:239], v[72:75]
	v_mfma_f32_16x16x32_bf16 v[68:71], v[160:163], v[236:239], v[68:71]
	s_setprio 0
	s_barrier
	s_add_i32 s61, s61, s73
	v_lshl_add_u64 v[168:169], s[50:51], 0, v[182:183]
	s_mov_b32 m0, s61
	ds_read_b128 v[164:167], v235 offset:16384
	ds_read_b128 v[198:201], v235 offset:17408
	ds_read_b128 v[202:205], v235 offset:18432
	ds_read_b128 v[206:209], v235 offset:19456
	ds_read_b128 v[210:213], v235 offset:20480
	ds_read_b128 v[214:217], v235 offset:21504
	ds_read_b128 v[218:221], v235 offset:22528
	ds_read_b128 v[236:239], v235 offset:23552
	global_load_lds_dwordx4 v[168:169], off
	s_add_i32 m0, s61, 0x2000
	s_add_u32 s78, s50, 0x80000
	v_lshl_add_u64 v[222:223], s[50:51], 0, v[186:187]
	s_addc_u32 s79, s51, 0
	s_add_i32 s61, s63, s73
	global_load_lds_dwordx4 v[222:223], off
	v_lshl_add_u64 v[2:3], s[78:79], 0, v[182:183]
	s_mov_b32 m0, s61
	v_lshl_add_u64 v[244:245], s[76:77], 0, v[180:181]
	global_load_lds_dwordx4 v[2:3], off
	v_lshl_add_u64 v[2:3], s[78:79], 0, v[186:187]
	s_add_i32 m0, s61, 0x2000
	v_lshl_add_u64 v[246:247], s[76:77], 0, v[184:185]
	global_load_lds_dwordx4 v[2:3], off
	s_mov_b32 m0, s82
	s_nop 0
	global_load_lds_dwordx4 v[244:245], off
	s_mov_b32 m0, s83
	s_nop 0
	global_load_lds_dwordx4 v[246:247], off
	s_waitcnt vmcnt(8)
	s_waitcnt lgkmcnt(0)
	s_barrier
; #define PG8_STAGE(bufoff, gbase, voff) do { _Pragma("unroll") for (int _i = 0; _i < 2; ++_i) \
;         __builtin_amdgcn_global_load_lds((const unsigned*)((const char*)(gbase) + (voff)[_i]), (PG8_LAS unsigned*)(lds + (bufoff) + ldsw + _i * 8192), 16, 0, 0); } while (0)
; #define PG8_LDA(dst, b, h) do { _Pragma("unroll") for (int m = 0; m < 4; ++m) _Pragma("unroll") for (int k = 0; k < 2; ++k) dst[m][k] = *(const PG8_LAS bf16x8*)(lds + PG8_SA(b, h) + aoff + m * 2048 + k * 1024); } while (0)
; #define PG8_LDB(dst, b, h) do { _Pragma("unroll") for (int n = 0; n < 2; ++n) _Pragma("unroll") for (int k = 0; k < 2; ++k) dst[n][k] = *(const PG8_LAS bf16x8*)(lds + PG8_SB(b, h) + boff + n * 2048 + k * 1024); } while (0)
; #define PG8_MMA(ai, bj, At, Bt) do { __builtin_amdgcn_s_setprio(1); _Pragma("unroll") for (int m = 0; m < 4; ++m) _Pragma("unroll") for (int n = 0; n < 2; ++n) _Pragma("unroll") for (int k = 0; k < 2; ++k) \
;         acc[ai][bj][m][n] = __builtin_amdgcn_mfma_f32_16x16x32_bf16(Bt[n][k], At[m][k], acc[ai][bj][m][n], 0, 0, 0); __builtin_amdgcn_s_setprio(0); } while (0)
; #define PG8_WAIT_V(n) asm volatile("s_waitcnt vmcnt(" #n ")" ::: "memory")
; #define PG8_WAIT_L(n) asm volatile("s_waitcnt lgkmcnt(" #n ")" ::: "memory")
; #define PG8_BAR __builtin_amdgcn_s_barrier()
; #define PG8_SCHED __builtin_amdgcn_sched_barrier(0)
; template <class Epi, class Sched, bool ALIGN_EPI = false, bool SP2 = false>
; __device__ __forceinline__ void gemm_phase(PG8_LAS unsigned char* lds, const Gemm g, const Sched& S, const Epi& E) {
;     ...
;             PG8_WAIT_V(8); PG8_WAIT_L(0); PG8_BAR; PG8_MMA(1, 0, At, B0); PG8_MMA(1, 1, At, B1); PG8_BAR; PG8_SCHED;
;             PG8_LDB(B0, 1, 0); PG8_LDB(B1, 1, 1); PG8_SCHED; PG8_LDA(At, 1, 0); PG8_STAGE(PG8_SA(0, 1), a2 + hstep, voffA);
;             PG8_WAIT_V(8); PG8_WAIT_L(0); PG8_BAR; PG8_MMA(0, 0, At, B0); PG8_MMA(0, 1, At, B1); PG8_BAR; PG8_SCHED;
;             PG8_LDA(At, 1, 1); PG8_STAGE(PG8_SB(1, 0), b3, voffB); PG8_STAGE(PG8_SB(1, 1), b3 + hstep, voffB); PG8_STAGE(PG8_SA(1, 0), a3, voffA);
	s_setprio 1
	s_waitcnt lgkmcnt(0)
	v_mfma_f32_16x16x32_bf16 v[64:67], v[124:127], v[164:167], v[64:67]
	v_mfma_f32_16x16x32_bf16 v[60:63], v[132:135], v[164:167], v[60:63]
	v_mfma_f32_16x16x32_bf16 v[48:51], v[124:127], v[202:205], v[48:51]
	v_mfma_f32_16x16x32_bf16 v[44:47], v[132:135], v[202:205], v[44:47]
	v_mfma_f32_16x16x32_bf16 v[32:35], v[124:127], v[210:213], v[32:35]
	v_mfma_f32_16x16x32_bf16 v[28:31], v[132:135], v[210:213], v[28:31]
	v_mfma_f32_16x16x32_bf16 v[16:19], v[124:127], v[218:221], v[16:19]
	v_mfma_f32_16x16x32_bf16 v[12:15], v[132:135], v[218:221], v[12:15]
	v_mfma_f32_16x16x32_bf16 v[64:67], v[128:131], v[198:201], v[64:67]
	v_mfma_f32_16x16x32_bf16 v[60:63], v[140:143], v[198:201], v[60:63]
	v_mfma_f32_16x16x32_bf16 v[48:51], v[128:131], v[206:209], v[48:51]
	v_mfma_f32_16x16x32_bf16 v[44:47], v[140:143], v[206:209], v[44:47]
	v_mfma_f32_16x16x32_bf16 v[32:35], v[128:131], v[214:217], v[32:35]
	v_mfma_f32_16x16x32_bf16 v[28:31], v[140:143], v[214:217], v[28:31]
	v_mfma_f32_16x16x32_bf16 v[16:19], v[128:131], v[236:239], v[16:19]
	v_mfma_f32_16x16x32_bf16 v[12:15], v[140:143], v[236:239], v[12:15]
	s_setprio 0
	s_setprio 1
	v_mfma_f32_16x16x32_bf16 v[56:59], v[148:151], v[164:167], v[56:59]
	v_mfma_f32_16x16x32_bf16 v[52:55], v[156:159], v[164:167], v[52:55]
	v_mfma_f32_16x16x32_bf16 v[40:43], v[148:151], v[202:205], v[40:43]
	v_mfma_f32_16x16x32_bf16 v[36:39], v[156:159], v[202:205], v[36:39]
	v_mfma_f32_16x16x32_bf16 v[24:27], v[148:151], v[210:213], v[24:27]
	v_mfma_f32_16x16x32_bf16 v[20:23], v[156:159], v[210:213], v[20:23]
	v_mfma_f32_16x16x32_bf16 v[8:11], v[148:151], v[218:221], v[8:11]
	v_mfma_f32_16x16x32_bf16 v[2:5], v[156:159], v[218:221], v[4:7]
	v_mfma_f32_16x16x32_bf16 v[56:59], v[152:155], v[198:201], v[56:59]
	v_mfma_f32_16x16x32_bf16 v[52:55], v[160:163], v[198:201], v[52:55]
	v_mfma_f32_16x16x32_bf16 v[40:43], v[152:155], v[206:209], v[40:43]
	v_mfma_f32_16x16x32_bf16 v[36:39], v[160:163], v[206:209], v[36:39]
	v_mfma_f32_16x16x32_bf16 v[24:27], v[152:155], v[214:217], v[24:27]
	v_mfma_f32_16x16x32_bf16 v[20:23], v[160:163], v[214:217], v[20:23]
	v_mfma_f32_16x16x32_bf16 v[8:11], v[152:155], v[236:239], v[8:11]
	v_mfma_f32_16x16x32_bf16 v[2:5], v[160:163], v[236:239], v[2:5]
	s_setprio 0
	s_barrier
	s_add_i32 s61, 0, 0x18000
	v_add_u32_e32 v0, s61, v234
	s_add_i32 s63, 0, 0x1c000
	ds_read_b128 v[124:127], v0
	ds_read_b128 v[128:131], v0 offset:1024
	ds_read_b128 v[132:135], v0 offset:2048
	ds_read_b128 v[140:143], v0 offset:3072
	v_add_u32_e32 v0, s63, v234
	ds_read_b128 v[148:151], v0
	ds_read_b128 v[152:155], v0 offset:1024
	ds_read_b128 v[156:159], v0 offset:2048
	ds_read_b128 v[160:163], v0 offset:3072
	s_add_u32 s76, s76, 0x80000
	s_addc_u32 s77, s77, 0
	s_mov_b32 m0, s84
	v_lshl_add_u64 v[6:7], s[76:77], 0, v[180:181]
	ds_read_b128 v[164:167], v235 offset:32768
	ds_read_b128 v[198:201], v235 offset:33792
	ds_read_b128 v[202:205], v235 offset:34816
	ds_read_b128 v[206:209], v235 offset:35840
	ds_read_b128 v[210:213], v235 offset:36864
	ds_read_b128 v[214:217], v235 offset:37888
	ds_read_b128 v[218:221], v235 offset:38912
	ds_read_b128 v[236:239], v235 offset:39936
	global_load_lds_dwordx4 v[6:7], off
	v_lshl_add_u64 v[6:7], s[76:77], 0, v[184:185]
	s_mov_b32 m0, s85
	s_nop 0
	global_load_lds_dwordx4 v[6:7], off
	s_waitcnt vmcnt(8)
	s_waitcnt lgkmcnt(0)
	s_barrier
	s_setprio 1
	s_waitcnt lgkmcnt(0)
	v_mfma_f32_16x16x32_bf16 v[144:147], v[124:127], v[164:167], v[144:147]
	v_mfma_f32_16x16x32_bf16 v[136:139], v[132:135], v[164:167], v[136:139]
	v_mfma_f32_16x16x32_bf16 v[112:115], v[124:127], v[202:205], v[112:115]
	v_mfma_f32_16x16x32_bf16 v[108:111], v[132:135], v[202:205], v[108:111]
	v_mfma_f32_16x16x32_bf16 v[96:99], v[124:127], v[210:213], v[96:99]
	v_mfma_f32_16x16x32_bf16 v[92:95], v[132:135], v[210:213], v[92:95]
	v_mfma_f32_16x16x32_bf16 v[80:83], v[124:127], v[218:221], v[80:83]
	v_mfma_f32_16x16x32_bf16 v[76:79], v[132:135], v[218:221], v[76:79]
	v_mfma_f32_16x16x32_bf16 v[144:147], v[128:131], v[198:201], v[144:147]
	v_mfma_f32_16x16x32_bf16 v[136:139], v[140:143], v[198:201], v[136:139]
	v_mfma_f32_16x16x32_bf16 v[112:115], v[128:131], v[206:209], v[112:115]
	v_mfma_f32_16x16x32_bf16 v[108:111], v[140:143], v[206:209], v[108:111]
	v_mfma_f32_16x16x32_bf16 v[96:99], v[128:131], v[214:217], v[96:99]
	v_mfma_f32_16x16x32_bf16 v[92:95], v[140:143], v[214:217], v[92:95]
	v_mfma_f32_16x16x32_bf16 v[80:83], v[128:131], v[236:239], v[80:83]
	v_mfma_f32_16x16x32_bf16 v[76:79], v[140:143], v[236:239], v[76:79]
	s_setprio 0
	s_setprio 1
	v_mfma_f32_16x16x32_bf16 v[120:123], v[148:151], v[164:167], v[120:123]
	v_mfma_f32_16x16x32_bf16 v[116:119], v[156:159], v[164:167], v[116:119]
	v_mfma_f32_16x16x32_bf16 v[104:107], v[148:151], v[202:205], v[104:107]
	v_mfma_f32_16x16x32_bf16 v[100:103], v[156:159], v[202:205], v[100:103]
	v_mfma_f32_16x16x32_bf16 v[88:91], v[148:151], v[210:213], v[88:91]
	v_mfma_f32_16x16x32_bf16 v[84:87], v[156:159], v[210:213], v[84:87]
	v_mfma_f32_16x16x32_bf16 v[72:75], v[148:151], v[218:221], v[72:75]
	v_mfma_f32_16x16x32_bf16 v[68:71], v[156:159], v[218:221], v[68:71]
	v_mfma_f32_16x16x32_bf16 v[120:123], v[152:155], v[198:201], v[120:123]
	v_mfma_f32_16x16x32_bf16 v[116:119], v[160:163], v[198:201], v[116:119]
	v_mfma_f32_16x16x32_bf16 v[104:107], v[152:155], v[206:209], v[104:107]
	v_mfma_f32_16x16x32_bf16 v[100:103], v[160:163], v[206:209], v[100:103]
	v_mfma_f32_16x16x32_bf16 v[88:91], v[152:155], v[214:217], v[88:91]
	v_mfma_f32_16x16x32_bf16 v[84:87], v[160:163], v[214:217], v[84:87]
	v_mfma_f32_16x16x32_bf16 v[72:75], v[152:155], v[236:239], v[72:75]
	v_mfma_f32_16x16x32_bf16 v[68:71], v[160:163], v[236:239], v[68:71]
	s_setprio 0
	s_barrier
; #define PG8_STAGE(bufoff, gbase, voff) do { _Pragma("unroll") for (int _i = 0; _i < 2; ++_i) \
;         __builtin_amdgcn_global_load_lds((const unsigned*)((const char*)(gbase) + (voff)[_i]), (PG8_LAS unsigned*)(lds + (bufoff) + ldsw + _i * 8192), 16, 0, 0); } while (0)
; #define PG8_LDA(dst, b, h) do { _Pragma("unroll") for (int m = 0; m < 4; ++m) _Pragma("unroll") for (int k = 0; k < 2; ++k) dst[m][k] = *(const PG8_LAS bf16x8*)(lds + PG8_SA(b, h) + aoff + m * 2048 + k * 1024); } while (0)
; #define PG8_MMA(ai, bj, At, Bt) do { __builtin_amdgcn_s_setprio(1); _Pragma("unroll") for (int m = 0; m < 4; ++m) _Pragma("unroll") for (int n = 0; n < 2; ++n) _Pragma("unroll") for (int k = 0; k < 2; ++k) \
;         acc[ai][bj][m][n] = __builtin_amdgcn_mfma_f32_16x16x32_bf16(Bt[n][k], At[m][k], acc[ai][bj][m][n], 0, 0, 0); __builtin_amdgcn_s_setprio(0); } while (0)
; #define PG8_WAIT_V(n) asm volatile("s_waitcnt vmcnt(" #n ")" ::: "memory")
; #define PG8_WAIT_L(n) asm volatile("s_waitcnt lgkmcnt(" #n ")" ::: "memory")
; #define PG8_BAR __builtin_amdgcn_s_barrier()
; #define PG8_SCHED __builtin_amdgcn_sched_barrier(0)
; template <class Epi, class Sched, bool ALIGN_EPI = false, bool SP2 = false>
; __device__ __forceinline__ void gemm_phase(PG8_LAS unsigned char* lds, const Gemm g, const Sched& S, const Epi& E) {
;     ...
;         for (int t = 0; t < nt; t += 2) {
;             const bool last = (t == nt - 2);
;             const char* a1 = cA + (size_t)(t + 1) * kstep;
;             const char* a2 = last ? nA : cA + (size_t)(t + 2) * kstep; const char* b2 = last ? nB : cB + (size_t)(t + 2) * kstep;
;             const char* a3 = a2 + kstep; const char* b3 = b2 + kstep;
;             if (last && has_next) S.a_ready(nxt);
;     ...
;             PG8_LDA(At, 1, 1); PG8_STAGE(PG8_SB(1, 0), b3, voffB); PG8_STAGE(PG8_SB(1, 1), b3 + hstep, voffB); PG8_STAGE(PG8_SA(1, 0), a3, voffA);
;             PG8_WAIT_V(8); PG8_WAIT_L(0); PG8_BAR; PG8_MMA(1, 0, At, B0); PG8_MMA(1, 1, At, B1); PG8_BAR; PG8_SCHED;
	s_add_i32 s61, s61, s73
	v_lshl_add_u64 v[6:7], v[168:169], 0, s[12:13]
	s_mov_b32 m0, s61
	ds_read_b128 v[164:167], v235 offset:49152
	ds_read_b128 v[198:201], v235 offset:50176
	ds_read_b128 v[202:205], v235 offset:51200
	ds_read_b128 v[206:209], v235 offset:52224
	ds_read_b128 v[210:213], v235 offset:53248
	ds_read_b128 v[214:217], v235 offset:54272
	ds_read_b128 v[218:221], v235 offset:55296
	ds_read_b128 v[236:239], v235 offset:56320
	global_load_lds_dwordx4 v[6:7], off
	s_add_i32 m0, s61, 0x2000
	s_add_u32 s50, s50, 0x80080
	v_lshl_add_u64 v[6:7], v[222:223], 0, s[12:13]
	s_addc_u32 s51, s51, 0
	s_add_i32 s61, s63, s73
	global_load_lds_dwordx4 v[6:7], off
	v_lshl_add_u64 v[6:7], s[50:51], 0, v[182:183]
	s_mov_b32 m0, s61
	s_nop 0
	global_load_lds_dwordx4 v[6:7], off
	v_lshl_add_u64 v[6:7], s[50:51], 0, v[186:187]
	s_add_i32 m0, s61, 0x2000
	s_nop 0
	global_load_lds_dwordx4 v[6:7], off
	v_lshl_add_u64 v[6:7], v[244:245], 0, s[12:13]
	s_mov_b32 m0, s87
	s_nop 0
	global_load_lds_dwordx4 v[6:7], off
	v_lshl_add_u64 v[6:7], v[246:247], 0, s[12:13]
	s_mov_b32 m0, s88
	s_nop 0
	global_load_lds_dwordx4 v[6:7], off
	s_add_i32 s58, s58, 2
	s_add_u32 s48, s48, 0x100
	s_addc_u32 s49, s49, 0
	s_add_u32 s39, s39, 0x100
	s_addc_u32 s47, s47, 0
	s_add_u32 s50, s48, 0xfff80080
	s_addc_u32 s51, s49, -1
	s_add_i32 s61, 0, 0x10000
	s_cmp_eq_u32 s58, 28
	s_cselect_b32 s77, s1, s51
	s_cselect_b32 s76, s24, s50
	s_cselect_b32 s51, s25, s47
	s_cselect_b32 s50, s38, s39
	s_add_i32 s63, 0, 0x14000
	s_waitcnt vmcnt(8)
	s_waitcnt lgkmcnt(0)
	s_barrier
	s_setprio 1
	s_waitcnt lgkmcnt(0)
	v_mfma_f32_16x16x32_bf16 v[64:67], v[124:127], v[164:167], v[64:67]
	v_mfma_f32_16x16x32_bf16 v[60:63], v[132:135], v[164:167], v[60:63]
	v_mfma_f32_16x16x32_bf16 v[48:51], v[124:127], v[202:205], v[48:51]
	v_mfma_f32_16x16x32_bf16 v[44:47], v[132:135], v[202:205], v[44:47]
	v_mfma_f32_16x16x32_bf16 v[32:35], v[124:127], v[210:213], v[32:35]
	v_mfma_f32_16x16x32_bf16 v[28:31], v[132:135], v[210:213], v[28:31]
	v_mfma_f32_16x16x32_bf16 v[16:19], v[124:127], v[218:221], v[16:19]
	v_mfma_f32_16x16x32_bf16 v[12:15], v[132:135], v[218:221], v[12:15]
	v_mfma_f32_16x16x32_bf16 v[64:67], v[128:131], v[198:201], v[64:67]
	v_mfma_f32_16x16x32_bf16 v[60:63], v[140:143], v[198:201], v[60:63]
	v_mfma_f32_16x16x32_bf16 v[48:51], v[128:131], v[206:209], v[48:51]
	v_mfma_f32_16x16x32_bf16 v[44:47], v[140:143], v[206:209], v[44:47]
	v_mfma_f32_16x16x32_bf16 v[32:35], v[128:131], v[214:217], v[32:35]
	v_mfma_f32_16x16x32_bf16 v[28:31], v[140:143], v[214:217], v[28:31]
	v_mfma_f32_16x16x32_bf16 v[16:19], v[128:131], v[236:239], v[16:19]
	v_mfma_f32_16x16x32_bf16 v[12:15], v[140:143], v[236:239], v[12:15]
	s_setprio 0
	s_setprio 1
	v_mfma_f32_16x16x32_bf16 v[56:59], v[148:151], v[164:167], v[56:59]
	v_mfma_f32_16x16x32_bf16 v[52:55], v[156:159], v[164:167], v[52:55]
	v_mfma_f32_16x16x32_bf16 v[40:43], v[148:151], v[202:205], v[40:43]
	v_mfma_f32_16x16x32_bf16 v[36:39], v[156:159], v[202:205], v[36:39]
	v_mfma_f32_16x16x32_bf16 v[24:27], v[148:151], v[210:213], v[24:27]
	v_mfma_f32_16x16x32_bf16 v[20:23], v[156:159], v[210:213], v[20:23]
	v_mfma_f32_16x16x32_bf16 v[6:9], v[148:151], v[218:221], v[8:11]
	v_mfma_f32_16x16x32_bf16 v[2:5], v[156:159], v[218:221], v[2:5]
	v_mfma_f32_16x16x32_bf16 v[56:59], v[152:155], v[198:201], v[56:59]
	v_mfma_f32_16x16x32_bf16 v[52:55], v[160:163], v[198:201], v[52:55]
	v_mfma_f32_16x16x32_bf16 v[40:43], v[152:155], v[206:209], v[40:43]
	v_mfma_f32_16x16x32_bf16 v[36:39], v[160:163], v[206:209], v[36:39]
	v_mfma_f32_16x16x32_bf16 v[24:27], v[152:155], v[214:217], v[24:27]
	v_mfma_f32_16x16x32_bf16 v[20:23], v[160:163], v[214:217], v[20:23]
	v_mfma_f32_16x16x32_bf16 v[8:11], v[152:155], v[236:239], v[6:9]
	v_mfma_f32_16x16x32_bf16 v[4:7], v[160:163], v[236:239], v[2:5]
	s_setprio 0
	s_barrier
	s_cmp_gt_u32 s58, 29
	s_cbranch_scc0 .Lqkv_kbody
	s_and_b64 vcc, exec, s[30:31]
	s_cbranch_vccz .LBB0_120
	s_barrier

; #define PG8_STAGE(bufoff, gbase, voff) do { _Pragma("unroll") for (int _i = 0; _i < 2; ++_i) \
;         __builtin_amdgcn_global_load_lds((const unsigned*)((const char*)(gbase) + (voff)[_i]), (PG8_LAS unsigned*)(lds + (bufoff) + ldsw + _i * 8192), 16, 0, 0); } while (0)
; #define PG8_LDA(dst, b, h) do { _Pragma("unroll") for (int m = 0; m < 4; ++m) _Pragma("unroll") for (int k = 0; k < 2; ++k) dst[m][k] = *(const PG8_LAS bf16x8*)(lds + PG8_SA(b, h) + aoff + m * 2048 + k * 1024); } while (0)
; #define PG8_LDB(dst, b, h) do { _Pragma("unroll") for (int n = 0; n < 2; ++n) _Pragma("unroll") for (int k = 0; k < 2; ++k) dst[n][k] = *(const PG8_LAS bf16x8*)(lds + PG8_SB(b, h) + boff + n * 2048 + k * 1024); } while (0)
; #define PG8_MMA(ai, bj, At, Bt) do { __builtin_amdgcn_s_setprio(1); _Pragma("unroll") for (int m = 0; m < 4; ++m) _Pragma("unroll") for (int n = 0; n < 2; ++n) _Pragma("unroll") for (int k = 0; k < 2; ++k) \
;         acc[ai][bj][m][n] = __builtin_amdgcn_mfma_f32_16x16x32_bf16(Bt[n][k], At[m][k], acc[ai][bj][m][n], 0, 0, 0); __builtin_amdgcn_s_setprio(0); } while (0)
; #define PG8_WAIT_V(n) asm volatile("s_waitcnt vmcnt(" #n ")" ::: "memory")
; #define PG8_WAIT_L(n) asm volatile("s_waitcnt lgkmcnt(" #n ")" ::: "memory")
; #define PG8_BAR __builtin_amdgcn_s_barrier()
; #define PG8_SCHED __builtin_amdgcn_sched_barrier(0)
; template <class Epi, class Sched, bool ALIGN_EPI = false, bool SP2 = false>
; __device__ __forceinline__ void gemm_phase(PG8_LAS unsigned char* lds, const Gemm g, const Sched& S, const Epi& E) {
;     ...
;             PG8_LDB(B0, 0, 0); PG8_LDB(B1, 0, 1); PG8_SCHED; PG8_LDA(At, 0, 0); PG8_STAGE(PG8_SA(1, 1), a1 + hstep, voffA);
;             PG8_WAIT_V(8); PG8_WAIT_L(0); PG8_BAR; PG8_MMA(0, 0, At, B0); PG8_MMA(0, 1, At, B1); PG8_BAR; PG8_SCHED;
;             PG8_LDA(At, 0, 1); PG8_STAGE(PG8_SB(0, 0), b2, voffB); PG8_STAGE(PG8_SB(0, 1), b2 + hstep, voffB); PG8_STAGE(PG8_SA(0, 0), a2, voffA);
;             PG8_WAIT_V(8); PG8_WAIT_L(0); PG8_BAR; PG8_MMA(1, 0, At, B0); PG8_MMA(1, 1, At, B1); PG8_BAR; PG8_SCHED;
.Lres_kbody:
	v_add_u32_e32 v142, s27, v185
	v_add_u32_e32 v168, s97, v185
	ds_read_b128 v[130:133], v142
	ds_read_b128 v[134:137], v142 offset:1024
	ds_read_b128 v[138:141], v142 offset:2048
	ds_read_b128 v[142:145], v142 offset:3072
	ds_read_b128 v[146:149], v168
	ds_read_b128 v[150:153], v168 offset:1024
	ds_read_b128 v[164:167], v168 offset:2048
	ds_read_b128 v[180:183], v168 offset:3072
	v_lshl_add_u64 v[168:169], s[44:45], 0, v[160:161]
	s_add_i32 m0, s83, 0xc000
	ds_read_b128 v[190:193], v187
	ds_read_b128 v[194:197], v187 offset:1024
	ds_read_b128 v[198:201], v187 offset:2048
	ds_read_b128 v[202:205], v187 offset:3072
	ds_read_b128 v[206:209], v187 offset:4096
	ds_read_b128 v[210:213], v187 offset:5120
	ds_read_b128 v[214:217], v187 offset:6144
	ds_read_b128 v[218:221], v187 offset:7168
	global_load_lds_dwordx4 v[168:169], off
	v_lshl_add_u64 v[168:169], s[44:45], 0, v[162:163]
	s_add_i32 m0, s83, 0xe000
	s_nop 0
	global_load_lds_dwordx4 v[168:169], off
	s_waitcnt vmcnt(8)
	s_waitcnt lgkmcnt(0)
	s_barrier
	s_setprio 1
	s_waitcnt lgkmcnt(0)
	v_mfma_f32_16x16x32_bf16 v[126:129], v[130:133], v[190:193], v[126:129]
	v_mfma_f32_16x16x32_bf16 v[122:125], v[138:141], v[190:193], v[122:125]
	v_mfma_f32_16x16x32_bf16 v[110:113], v[130:133], v[198:201], v[110:113]
	v_mfma_f32_16x16x32_bf16 v[106:109], v[138:141], v[198:201], v[106:109]
	v_mfma_f32_16x16x32_bf16 v[94:97], v[130:133], v[206:209], v[94:97]
	v_mfma_f32_16x16x32_bf16 v[90:93], v[138:141], v[206:209], v[90:93]
	v_mfma_f32_16x16x32_bf16 v[78:81], v[130:133], v[214:217], v[78:81]
	v_mfma_f32_16x16x32_bf16 v[74:77], v[138:141], v[214:217], v[74:77]
	v_mfma_f32_16x16x32_bf16 v[126:129], v[134:137], v[194:197], v[126:129]
	v_mfma_f32_16x16x32_bf16 v[122:125], v[142:145], v[194:197], v[122:125]
	v_mfma_f32_16x16x32_bf16 v[110:113], v[134:137], v[202:205], v[110:113]
	v_mfma_f32_16x16x32_bf16 v[106:109], v[142:145], v[202:205], v[106:109]
	v_mfma_f32_16x16x32_bf16 v[94:97], v[134:137], v[210:213], v[94:97]
	v_mfma_f32_16x16x32_bf16 v[90:93], v[142:145], v[210:213], v[90:93]
	v_mfma_f32_16x16x32_bf16 v[78:81], v[134:137], v[218:221], v[78:81]
	v_mfma_f32_16x16x32_bf16 v[74:77], v[142:145], v[218:221], v[74:77]
	s_setprio 0
	s_setprio 1
	v_mfma_f32_16x16x32_bf16 v[118:121], v[146:149], v[190:193], v[118:121]
	v_mfma_f32_16x16x32_bf16 v[114:117], v[164:167], v[190:193], v[114:117]
	v_mfma_f32_16x16x32_bf16 v[102:105], v[146:149], v[198:201], v[102:105]
	v_mfma_f32_16x16x32_bf16 v[98:101], v[164:167], v[198:201], v[98:101]
	v_mfma_f32_16x16x32_bf16 v[86:89], v[146:149], v[206:209], v[86:89]
	v_mfma_f32_16x16x32_bf16 v[82:85], v[164:167], v[206:209], v[82:85]
	v_mfma_f32_16x16x32_bf16 v[70:73], v[146:149], v[214:217], v[70:73]
	v_mfma_f32_16x16x32_bf16 v[66:69], v[164:167], v[214:217], v[66:69]
	v_mfma_f32_16x16x32_bf16 v[118:121], v[150:153], v[194:197], v[118:121]
	v_mfma_f32_16x16x32_bf16 v[114:117], v[180:183], v[194:197], v[114:117]
	v_mfma_f32_16x16x32_bf16 v[102:105], v[150:153], v[202:205], v[102:105]
	v_mfma_f32_16x16x32_bf16 v[98:101], v[180:183], v[202:205], v[98:101]
	v_mfma_f32_16x16x32_bf16 v[86:89], v[150:153], v[210:213], v[86:89]
	v_mfma_f32_16x16x32_bf16 v[82:85], v[180:183], v[210:213], v[82:85]
	v_mfma_f32_16x16x32_bf16 v[70:73], v[150:153], v[218:221], v[70:73]
	v_mfma_f32_16x16x32_bf16 v[66:69], v[180:183], v[218:221], v[66:69]
	s_setprio 0
	s_barrier
	s_add_i32 s27, s27, s82
	v_lshl_add_u64 v[168:169], vcc, 0, v[0:1]
	s_mov_b32 m0, s27
	ds_read_b128 v[190:193], v187 offset:16384
	ds_read_b128 v[194:197], v187 offset:17408
	ds_read_b128 v[198:201], v187 offset:18432
	ds_read_b128 v[202:205], v187 offset:19456
	ds_read_b128 v[206:209], v187 offset:20480
	ds_read_b128 v[210:213], v187 offset:21504
	ds_read_b128 v[214:217], v187 offset:22528
	ds_read_b128 v[218:221], v187 offset:23552
	global_load_lds_dwordx4 v[168:169], off
	s_add_i32 m0, s27, 0x2000
	v_lshl_add_u64 v[222:223], vcc, 0, v[154:155]
	s_add_u32 vcc_lo, vcc_lo, s70
	s_addc_u32 vcc_hi, vcc_hi, 0
	s_add_i32 s27, s97, s82
	global_load_lds_dwordx4 v[222:223], off
	v_lshl_add_u64 v[232:233], vcc, 0, v[0:1]
	s_mov_b32 m0, s27
	v_lshl_add_u64 v[234:235], vcc, 0, v[154:155]
	global_load_lds_dwordx4 v[232:233], off
	s_add_i32 m0, s27, 0x2000
	v_lshl_add_u64 v[236:237], s[74:75], 0, v[158:159]
	global_load_lds_dwordx4 v[234:235], off
	s_mov_b32 m0, s83
	v_lshl_add_u64 v[238:239], s[74:75], 0, v[156:157]
	global_load_lds_dwordx4 v[236:237], off
	s_mov_b32 m0, s84
	s_nop 0
	global_load_lds_dwordx4 v[238:239], off
	s_waitcnt vmcnt(8)
	s_waitcnt lgkmcnt(0)
	s_barrier
; #define PG8_STAGE(bufoff, gbase, voff) do { _Pragma("unroll") for (int _i = 0; _i < 2; ++_i) \
;         __builtin_amdgcn_global_load_lds((const unsigned*)((const char*)(gbase) + (voff)[_i]), (PG8_LAS unsigned*)(lds + (bufoff) + ldsw + _i * 8192), 16, 0, 0); } while (0)
; #define PG8_LDA(dst, b, h) do { _Pragma("unroll") for (int m = 0; m < 4; ++m) _Pragma("unroll") for (int k = 0; k < 2; ++k) dst[m][k] = *(const PG8_LAS bf16x8*)(lds + PG8_SA(b, h) + aoff + m * 2048 + k * 1024); } while (0)
; #define PG8_LDB(dst, b, h) do { _Pragma("unroll") for (int n = 0; n < 2; ++n) _Pragma("unroll") for (int k = 0; k < 2; ++k) dst[n][k] = *(const PG8_LAS bf16x8*)(lds + PG8_SB(b, h) + boff + n * 2048 + k * 1024); } while (0)
; #define PG8_MMA(ai, bj, At, Bt) do { __builtin_amdgcn_s_setprio(1); _Pragma("unroll") for (int m = 0; m < 4; ++m) _Pragma("unroll") for (int n = 0; n < 2; ++n) _Pragma("unroll") for (int k = 0; k < 2; ++k) \
;         acc[ai][bj][m][n] = __builtin_amdgcn_mfma_f32_16x16x32_bf16(Bt[n][k], At[m][k], acc[ai][bj][m][n], 0, 0, 0); __builtin_amdgcn_s_setprio(0); } while (0)
; #define PG8_WAIT_V(n) asm volatile("s_waitcnt vmcnt(" #n ")" ::: "memory")
; #define PG8_WAIT_L(n) asm volatile("s_waitcnt lgkmcnt(" #n ")" ::: "memory")
; #define PG8_BAR __builtin_amdgcn_s_barrier()
; #define PG8_SCHED __builtin_amdgcn_sched_barrier(0)
; template <class Epi, class Sched, bool ALIGN_EPI = false, bool SP2 = false>
; __device__ __forceinline__ void gemm_phase(PG8_LAS unsigned char* lds, const Gemm g, const Sched& S, const Epi& E) {
;     ...
;             PG8_WAIT_V(8); PG8_WAIT_L(0); PG8_BAR; PG8_MMA(1, 0, At, B0); PG8_MMA(1, 1, At, B1); PG8_BAR; PG8_SCHED;
;             PG8_LDB(B0, 1, 0); PG8_LDB(B1, 1, 1); PG8_SCHED; PG8_LDA(At, 1, 0); PG8_STAGE(PG8_SA(0, 1), a2 + hstep, voffA);
;             PG8_WAIT_V(8); PG8_WAIT_L(0); PG8_BAR; PG8_MMA(0, 0, At, B0); PG8_MMA(0, 1, At, B1); PG8_BAR; PG8_SCHED;
;             PG8_LDA(At, 1, 1); PG8_STAGE(PG8_SB(1, 0), b3, voffB); PG8_STAGE(PG8_SB(1, 1), b3 + hstep, voffB); PG8_STAGE(PG8_SA(1, 0), a3, voffA);
	s_setprio 1
	s_waitcnt lgkmcnt(0)
	v_mfma_f32_16x16x32_bf16 v[62:65], v[130:133], v[190:193], v[62:65]
	v_mfma_f32_16x16x32_bf16 v[58:61], v[138:141], v[190:193], v[58:61]
	v_mfma_f32_16x16x32_bf16 v[46:49], v[130:133], v[198:201], v[46:49]
	v_mfma_f32_16x16x32_bf16 v[42:45], v[138:141], v[198:201], v[42:45]
	v_mfma_f32_16x16x32_bf16 v[30:33], v[130:133], v[206:209], v[30:33]
	v_mfma_f32_16x16x32_bf16 v[26:29], v[138:141], v[206:209], v[26:29]
	v_mfma_f32_16x16x32_bf16 v[14:17], v[130:133], v[214:217], v[14:17]
	v_mfma_f32_16x16x32_bf16 v[10:13], v[138:141], v[214:217], v[10:13]
	v_mfma_f32_16x16x32_bf16 v[62:65], v[134:137], v[194:197], v[62:65]
	v_mfma_f32_16x16x32_bf16 v[58:61], v[142:145], v[194:197], v[58:61]
	v_mfma_f32_16x16x32_bf16 v[46:49], v[134:137], v[202:205], v[46:49]
	v_mfma_f32_16x16x32_bf16 v[42:45], v[142:145], v[202:205], v[42:45]
	v_mfma_f32_16x16x32_bf16 v[30:33], v[134:137], v[210:213], v[30:33]
	v_mfma_f32_16x16x32_bf16 v[26:29], v[142:145], v[210:213], v[26:29]
	v_mfma_f32_16x16x32_bf16 v[14:17], v[134:137], v[218:221], v[14:17]
	v_mfma_f32_16x16x32_bf16 v[10:13], v[142:145], v[218:221], v[10:13]
	s_setprio 0
	s_setprio 1
	v_mfma_f32_16x16x32_bf16 v[54:57], v[146:149], v[190:193], v[54:57]
	v_mfma_f32_16x16x32_bf16 v[50:53], v[164:167], v[190:193], v[50:53]
	v_mfma_f32_16x16x32_bf16 v[38:41], v[146:149], v[198:201], v[38:41]
	v_mfma_f32_16x16x32_bf16 v[34:37], v[164:167], v[198:201], v[34:37]
	v_mfma_f32_16x16x32_bf16 v[22:25], v[146:149], v[206:209], v[22:25]
	v_mfma_f32_16x16x32_bf16 v[18:21], v[164:167], v[206:209], v[18:21]
	v_mfma_f32_16x16x32_bf16 v[6:9], v[146:149], v[214:217], v[6:9]
	v_mfma_f32_16x16x32_bf16 v[2:5], v[164:167], v[214:217], v[2:5]
	v_mfma_f32_16x16x32_bf16 v[54:57], v[150:153], v[194:197], v[54:57]
	v_mfma_f32_16x16x32_bf16 v[50:53], v[180:183], v[194:197], v[50:53]
	v_mfma_f32_16x16x32_bf16 v[38:41], v[150:153], v[202:205], v[38:41]
	v_mfma_f32_16x16x32_bf16 v[34:37], v[180:183], v[202:205], v[34:37]
	v_mfma_f32_16x16x32_bf16 v[22:25], v[150:153], v[210:213], v[22:25]
	v_mfma_f32_16x16x32_bf16 v[18:21], v[180:183], v[210:213], v[18:21]
	v_mfma_f32_16x16x32_bf16 v[6:9], v[150:153], v[218:221], v[6:9]
	v_mfma_f32_16x16x32_bf16 v[2:5], v[180:183], v[218:221], v[2:5]
	s_setprio 0
	s_barrier
	s_add_i32 s27, 0, 0x18000
	s_add_i32 s97, 0, 0x1c000
	v_add_u32_e32 v142, s27, v185
	v_add_u32_e32 v180, s97, v185
	ds_read_b128 v[130:133], v142
	ds_read_b128 v[134:137], v142 offset:1024
	ds_read_b128 v[138:141], v142 offset:2048
	ds_read_b128 v[142:145], v142 offset:3072
	ds_read_b128 v[146:149], v180
	ds_read_b128 v[150:153], v180 offset:1024
	ds_read_b128 v[164:167], v180 offset:2048
	ds_read_b128 v[180:183], v180 offset:3072
	s_add_u32 s74, s74, s70
	s_addc_u32 s75, s75, 0
	s_mov_b32 m0, s85
	v_lshl_add_u64 v[244:245], s[74:75], 0, v[158:159]
	ds_read_b128 v[190:193], v187 offset:32768
	ds_read_b128 v[194:197], v187 offset:33792
	ds_read_b128 v[198:201], v187 offset:34816
	ds_read_b128 v[202:205], v187 offset:35840
	ds_read_b128 v[206:209], v187 offset:36864
	ds_read_b128 v[210:213], v187 offset:37888
	ds_read_b128 v[214:217], v187 offset:38912
	ds_read_b128 v[218:221], v187 offset:39936
	global_load_lds_dwordx4 v[244:245], off
	v_lshl_add_u64 v[244:245], s[74:75], 0, v[156:157]
	s_mov_b32 m0, s86
	s_nop 0
	global_load_lds_dwordx4 v[244:245], off
	s_waitcnt vmcnt(8)
	s_waitcnt lgkmcnt(0)
	s_barrier
	s_setprio 1
	s_waitcnt lgkmcnt(0)
	v_mfma_f32_16x16x32_bf16 v[126:129], v[130:133], v[190:193], v[126:129]
	v_mfma_f32_16x16x32_bf16 v[122:125], v[138:141], v[190:193], v[122:125]
	v_mfma_f32_16x16x32_bf16 v[110:113], v[130:133], v[198:201], v[110:113]
	v_mfma_f32_16x16x32_bf16 v[106:109], v[138:141], v[198:201], v[106:109]
	v_mfma_f32_16x16x32_bf16 v[94:97], v[130:133], v[206:209], v[94:97]
	v_mfma_f32_16x16x32_bf16 v[90:93], v[138:141], v[206:209], v[90:93]
	v_mfma_f32_16x16x32_bf16 v[78:81], v[130:133], v[214:217], v[78:81]
	v_mfma_f32_16x16x32_bf16 v[74:77], v[138:141], v[214:217], v[74:77]
	v_mfma_f32_16x16x32_bf16 v[126:129], v[134:137], v[194:197], v[126:129]
	v_mfma_f32_16x16x32_bf16 v[122:125], v[142:145], v[194:197], v[122:125]
	v_mfma_f32_16x16x32_bf16 v[110:113], v[134:137], v[202:205], v[110:113]
	v_mfma_f32_16x16x32_bf16 v[106:109], v[142:145], v[202:205], v[106:109]
	v_mfma_f32_16x16x32_bf16 v[94:97], v[134:137], v[210:213], v[94:97]
	v_mfma_f32_16x16x32_bf16 v[90:93], v[142:145], v[210:213], v[90:93]
	v_mfma_f32_16x16x32_bf16 v[78:81], v[134:137], v[218:221], v[78:81]
	v_mfma_f32_16x16x32_bf16 v[74:77], v[142:145], v[218:221], v[74:77]
	s_setprio 0
	s_setprio 1
	v_mfma_f32_16x16x32_bf16 v[118:121], v[146:149], v[190:193], v[118:121]
	v_mfma_f32_16x16x32_bf16 v[114:117], v[164:167], v[190:193], v[114:117]
	v_mfma_f32_16x16x32_bf16 v[102:105], v[146:149], v[198:201], v[102:105]
	v_mfma_f32_16x16x32_bf16 v[98:101], v[164:167], v[198:201], v[98:101]
	v_mfma_f32_16x16x32_bf16 v[86:89], v[146:149], v[206:209], v[86:89]
	v_mfma_f32_16x16x32_bf16 v[82:85], v[164:167], v[206:209], v[82:85]
	v_mfma_f32_16x16x32_bf16 v[70:73], v[146:149], v[214:217], v[70:73]
	v_mfma_f32_16x16x32_bf16 v[66:69], v[164:167], v[214:217], v[66:69]
	v_mfma_f32_16x16x32_bf16 v[118:121], v[150:153], v[194:197], v[118:121]
	v_mfma_f32_16x16x32_bf16 v[114:117], v[180:183], v[194:197], v[114:117]
	v_mfma_f32_16x16x32_bf16 v[102:105], v[150:153], v[202:205], v[102:105]
	v_mfma_f32_16x16x32_bf16 v[98:101], v[180:183], v[202:205], v[98:101]
	v_mfma_f32_16x16x32_bf16 v[86:89], v[150:153], v[210:213], v[86:89]
	v_mfma_f32_16x16x32_bf16 v[82:85], v[180:183], v[210:213], v[82:85]
	v_mfma_f32_16x16x32_bf16 v[70:73], v[150:153], v[218:221], v[70:73]
	v_mfma_f32_16x16x32_bf16 v[66:69], v[180:183], v[218:221], v[66:69]
	s_setprio 0
	s_barrier
; #define PG8_STAGE(bufoff, gbase, voff) do { _Pragma("unroll") for (int _i = 0; _i < 2; ++_i) \
;         __builtin_amdgcn_global_load_lds((const unsigned*)((const char*)(gbase) + (voff)[_i]), (PG8_LAS unsigned*)(lds + (bufoff) + ldsw + _i * 8192), 16, 0, 0); } while (0)
; #define PG8_LDA(dst, b, h) do { _Pragma("unroll") for (int m = 0; m < 4; ++m) _Pragma("unroll") for (int k = 0; k < 2; ++k) dst[m][k] = *(const PG8_LAS bf16x8*)(lds + PG8_SA(b, h) + aoff + m * 2048 + k * 1024); } while (0)
; #define PG8_MMA(ai, bj, At, Bt) do { __builtin_amdgcn_s_setprio(1); _Pragma("unroll") for (int m = 0; m < 4; ++m) _Pragma("unroll") for (int n = 0; n < 2; ++n) _Pragma("unroll") for (int k = 0; k < 2; ++k) \
;         acc[ai][bj][m][n] = __builtin_amdgcn_mfma_f32_16x16x32_bf16(Bt[n][k], At[m][k], acc[ai][bj][m][n], 0, 0, 0); __builtin_amdgcn_s_setprio(0); } while (0)
; #define PG8_WAIT_V(n) asm volatile("s_waitcnt vmcnt(" #n ")" ::: "memory")
; #define PG8_WAIT_L(n) asm volatile("s_waitcnt lgkmcnt(" #n ")" ::: "memory")
; #define PG8_BAR __builtin_amdgcn_s_barrier()
; #define PG8_SCHED __builtin_amdgcn_sched_barrier(0)
; template <class Epi, class Sched, bool ALIGN_EPI = false, bool SP2 = false>
; __device__ __forceinline__ void gemm_phase(PG8_LAS unsigned char* lds, const Gemm g, const Sched& S, const Epi& E) {
;     ...
;         for (int t = 0; t < nt; t += 2) {
;             const bool last = (t == nt - 2);
;             const char* a1 = cA + (size_t)(t + 1) * kstep;
;             const char* a2 = last ? nA : cA + (size_t)(t + 2) * kstep; const char* b2 = last ? nB : cB + (size_t)(t + 2) * kstep;
;             const char* a3 = a2 + kstep; const char* b3 = b2 + kstep;
;             if (last && has_next) S.a_ready(nxt);
;     ...
;             PG8_LDA(At, 1, 1); PG8_STAGE(PG8_SB(1, 0), b3, voffB); PG8_STAGE(PG8_SB(1, 1), b3 + hstep, voffB); PG8_STAGE(PG8_SA(1, 0), a3, voffA);
;             PG8_WAIT_V(8); PG8_WAIT_L(0); PG8_BAR; PG8_MMA(1, 0, At, B0); PG8_MMA(1, 1, At, B1); PG8_BAR; PG8_SCHED;
	s_add_i32 s27, s27, s82
	v_lshl_add_u64 v[168:169], v[168:169], 0, s[12:13]
	s_mov_b32 m0, s27
	ds_read_b128 v[190:193], v187 offset:49152
	ds_read_b128 v[194:197], v187 offset:50176
	ds_read_b128 v[198:201], v187 offset:51200
	ds_read_b128 v[202:205], v187 offset:52224
	ds_read_b128 v[206:209], v187 offset:53248
	ds_read_b128 v[210:213], v187 offset:54272
	ds_read_b128 v[214:217], v187 offset:55296
	ds_read_b128 v[218:221], v187 offset:56320
	global_load_lds_dwordx4 v[168:169], off
	v_lshl_add_u64 v[168:169], v[222:223], 0, s[12:13]
	s_add_i32 m0, s27, 0x2000
	s_add_i32 s27, s97, s82
	global_load_lds_dwordx4 v[168:169], off
	v_lshl_add_u64 v[168:169], v[232:233], 0, s[12:13]
	s_mov_b32 m0, s27
	s_nop 0
	global_load_lds_dwordx4 v[168:169], off
	v_lshl_add_u64 v[168:169], v[234:235], 0, s[12:13]
	s_add_i32 m0, s27, 0x2000
	s_nop 0
	global_load_lds_dwordx4 v[168:169], off
	v_lshl_add_u64 v[168:169], v[236:237], 0, s[12:13]
	s_mov_b32 m0, s89
	s_nop 0
	global_load_lds_dwordx4 v[168:169], off
	v_lshl_add_u64 v[168:169], v[238:239], 0, s[12:13]
	s_mov_b32 m0, s90
	s_nop 0
	global_load_lds_dwordx4 v[168:169], off
	s_add_u32 s44, s44, 0x100
	s_addc_u32 s45, s45, 0
	s_add_u32 s94, s94, 0x100
	s_addc_u32 s95, s95, 0
	s_cmp_ge_u32 s96, s88
	s_cselect_b32 s98, 1, 0
	s_mov_b32 s74, s96
	s_add_i32 s96, s74, 2
	s_add_u32 s97, s44, 0x80
	s_addc_u32 s75, s45, 0
	s_add_i32 s27, 0, 0x10000
	s_cmp_eq_u32 s91, s74
	s_cselect_b32 s75, s24, s75
	s_cselect_b32 s74, s25, s97
	s_cselect_b32 vcc_hi, s53, s95
	s_cselect_b32 vcc_lo, s61, s94
	s_add_i32 s97, 0, 0x14000
	s_waitcnt vmcnt(8)
	s_waitcnt lgkmcnt(0)
	s_barrier
	s_setprio 1
	s_waitcnt lgkmcnt(0)
	v_mfma_f32_16x16x32_bf16 v[62:65], v[130:133], v[190:193], v[62:65]
	v_mfma_f32_16x16x32_bf16 v[58:61], v[138:141], v[190:193], v[58:61]
	v_mfma_f32_16x16x32_bf16 v[46:49], v[130:133], v[198:201], v[46:49]
	v_mfma_f32_16x16x32_bf16 v[42:45], v[138:141], v[198:201], v[42:45]
	v_mfma_f32_16x16x32_bf16 v[30:33], v[130:133], v[206:209], v[30:33]
	v_mfma_f32_16x16x32_bf16 v[26:29], v[138:141], v[206:209], v[26:29]
	v_mfma_f32_16x16x32_bf16 v[14:17], v[130:133], v[214:217], v[14:17]
	v_mfma_f32_16x16x32_bf16 v[10:13], v[138:141], v[214:217], v[10:13]
	v_mfma_f32_16x16x32_bf16 v[62:65], v[134:137], v[194:197], v[62:65]
	v_mfma_f32_16x16x32_bf16 v[58:61], v[142:145], v[194:197], v[58:61]
	v_mfma_f32_16x16x32_bf16 v[46:49], v[134:137], v[202:205], v[46:49]
	v_mfma_f32_16x16x32_bf16 v[42:45], v[142:145], v[202:205], v[42:45]
	v_mfma_f32_16x16x32_bf16 v[30:33], v[134:137], v[210:213], v[30:33]
	v_mfma_f32_16x16x32_bf16 v[26:29], v[142:145], v[210:213], v[26:29]
	v_mfma_f32_16x16x32_bf16 v[14:17], v[134:137], v[218:221], v[14:17]
	v_mfma_f32_16x16x32_bf16 v[10:13], v[142:145], v[218:221], v[10:13]
	s_setprio 0
	s_setprio 1
	v_mfma_f32_16x16x32_bf16 v[54:57], v[146:149], v[190:193], v[54:57]
	v_mfma_f32_16x16x32_bf16 v[50:53], v[164:167], v[190:193], v[50:53]
	v_mfma_f32_16x16x32_bf16 v[38:41], v[146:149], v[198:201], v[38:41]
	v_mfma_f32_16x16x32_bf16 v[34:37], v[164:167], v[198:201], v[34:37]
	v_mfma_f32_16x16x32_bf16 v[22:25], v[146:149], v[206:209], v[22:25]
	v_mfma_f32_16x16x32_bf16 v[18:21], v[164:167], v[206:209], v[18:21]
	v_mfma_f32_16x16x32_bf16 v[6:9], v[146:149], v[214:217], v[6:9]
	v_mfma_f32_16x16x32_bf16 v[2:5], v[164:167], v[214:217], v[2:5]
	v_mfma_f32_16x16x32_bf16 v[54:57], v[150:153], v[194:197], v[54:57]
	v_mfma_f32_16x16x32_bf16 v[50:53], v[180:183], v[194:197], v[50:53]
	v_mfma_f32_16x16x32_bf16 v[38:41], v[150:153], v[202:205], v[38:41]
	v_mfma_f32_16x16x32_bf16 v[34:37], v[180:183], v[202:205], v[34:37]
	v_mfma_f32_16x16x32_bf16 v[22:25], v[150:153], v[210:213], v[22:25]
	v_mfma_f32_16x16x32_bf16 v[18:21], v[180:183], v[210:213], v[18:21]
	v_mfma_f32_16x16x32_bf16 v[6:9], v[150:153], v[218:221], v[6:9]
	v_mfma_f32_16x16x32_bf16 v[2:5], v[180:183], v[218:221], v[2:5]
	s_setprio 0
	s_barrier
	s_cmp_lg_u32 s98, 0
	s_cbranch_scc0 .Lres_kbody
	s_and_b64 vcc, exec, s[48:49]
	s_cbranch_vccz .LBB0_1430
	s_barrier
